# adds: sample SSD recurrence computes the 32 rows of a round first, then reduces all 32 partial sums with one shared 6-step wave butterfly (same per-row arithmetic order)
# speedup vs baseline: 1.0033x; 1.0033x over previous
.LBB0_334:
	s_lshl_b32 s2, s17, 7
	s_lshl_b64 s[10:11], s[2:3], 2
	s_waitcnt lgkmcnt(0)
	v_lshl_add_u64 v[18:19], v[14:15], 0, s[10:11]
	global_load_dwordx2 v[72:73], v[18:19], off offset:2048
	global_load_dwordx2 v[70:71], v[18:19], off offset:2560
	global_load_dwordx2 v[68:69], v[18:19], off offset:3072
	global_load_dwordx2 v[64:65], v[18:19], off offset:3584
	global_load_dwordx2 v[78:79], v[18:19], off offset:512
	global_load_dwordx2 v[76:77], v[18:19], off offset:1024
	global_load_dwordx2 v[74:75], v[18:19], off offset:1536
	global_load_dwordx2 v[88:89], v[18:19], off
	v_add_co_u32_e32 v20, vcc, 0x1000, v18
	s_movk_i32 s18, 0x2000
	s_nop 0
	v_addc_co_u32_e32 v21, vcc, 0, v19, vcc
	global_load_dwordx2 v[66:67], v[20:21], off
	global_load_dwordx2 v[62:63], v[20:21], off offset:512
	global_load_dwordx2 v[60:61], v[20:21], off offset:1024
	global_load_dwordx2 v[58:59], v[20:21], off offset:1536
	global_load_dwordx2 v[56:57], v[20:21], off offset:2048
	global_load_dwordx2 v[54:55], v[20:21], off offset:2560
	global_load_dwordx2 v[52:53], v[20:21], off offset:3072
	global_load_dwordx2 v[50:51], v[20:21], off offset:3584
	v_add_co_u32_e32 v20, vcc, s18, v18
	s_movk_i32 s18, 0x3000
	s_nop 0
	v_addc_co_u32_e32 v21, vcc, 0, v19, vcc
	v_add_co_u32_e32 v18, vcc, s18, v18
	v_or_b32_e32 v87, s17, v9
	s_nop 0
	v_addc_co_u32_e32 v19, vcc, 0, v19, vcc
	global_load_dwordx2 v[46:47], v[20:21], off offset:512
	global_load_dwordx2 v[44:45], v[20:21], off offset:1024
	global_load_dwordx2 v[42:43], v[20:21], off offset:1536
	global_load_dwordx2 v[40:41], v[20:21], off offset:2048
	global_load_dwordx2 v[48:49], v[18:19], off offset:-4096
	global_load_dwordx2 v[38:39], v[20:21], off offset:2560
	global_load_dwordx2 v[36:37], v[20:21], off offset:3072
	global_load_dwordx2 v[34:35], v[20:21], off offset:3584
	global_load_dwordx2 v[32:33], v[18:19], off
	global_load_dwordx2 v[30:31], v[18:19], off offset:512
	global_load_dwordx2 v[28:29], v[18:19], off offset:1024
	global_load_dwordx2 v[26:27], v[18:19], off offset:1536
	global_load_dwordx2 v[24:25], v[18:19], off offset:2048
	global_load_dwordx2 v[22:23], v[18:19], off offset:2560
	global_load_dwordx2 v[20:21], v[18:19], off offset:3072
	s_nop 0
	global_load_dwordx2 v[18:19], v[18:19], off offset:3584
	v_lshl_add_u32 v87, v87, 2, 0
	s_waitcnt vmcnt(0)
	ds_read_b32 v96, v87
	ds_read_b32 v97, v87 offset:4
	ds_read_b32 v98, v87 offset:8
	ds_read_b32 v99, v87 offset:12
	ds_read_b32 v100, v87 offset:16
	ds_read_b32 v101, v87 offset:20
	ds_read_b32 v102, v87 offset:24
	ds_read_b32 v103, v87 offset:28
	ds_read_b32 v104, v87 offset:32
	ds_read_b32 v105, v87 offset:36
	ds_read_b32 v106, v87 offset:40
	ds_read_b32 v107, v87 offset:44
	ds_read_b32 v108, v87 offset:48
	ds_read_b32 v109, v87 offset:52
	ds_read_b32 v110, v87 offset:56
	ds_read_b32 v111, v87 offset:60
	s_waitcnt lgkmcnt(0)
	ds_read_b32 v112, v87 offset:64
	ds_read_b32 v113, v87 offset:68
	ds_read_b32 v114, v87 offset:72
	ds_read_b32 v115, v87 offset:76
	ds_read_b32 v116, v87 offset:80
	ds_read_b32 v117, v87 offset:84
	ds_read_b32 v118, v87 offset:88
	ds_read_b32 v119, v87 offset:92
	ds_read_b32 v120, v87 offset:96
	ds_read_b32 v121, v87 offset:100
	ds_read_b32 v122, v87 offset:104
	ds_read_b32 v123, v87 offset:108
	ds_read_b32 v124, v87 offset:112
	ds_read_b32 v125, v87 offset:116
	ds_read_b32 v126, v87 offset:120
	ds_read_b32 v127, v87 offset:124
	s_waitcnt lgkmcnt(0)
	v_mul_f32_e32 v128, v81, v96
	s_lshl_b64 s[10:11], s[2:3], 2
	v_lshl_add_u64 v[92:93], v[16:17], 0, s[10:11]
	v_pk_mul_f32 v[128:129], v[2:3], v[128:129] op_sel_hi:[1,0]
	s_nop 0
	v_pk_fma_f32 v[128:129], v[12:13], v[88:89], v[128:129]
	global_store_dwordx2 v[92:93], v[128:129], off
	v_mul_f32_e32 v96, v5, v129
	v_fmac_f32_e32 v96, v4, v128
	v_mul_f32_e32 v130, v81, v97
	s_or_b32 s10, s2, 0x80
	s_mov_b32 s11, s3
	v_lshl_add_u64 v[92:93], s[10:11], 2, v[16:17]
	v_pk_mul_f32 v[130:131], v[2:3], v[130:131] op_sel_hi:[1,0]
	s_nop 0
	v_pk_fma_f32 v[130:131], v[12:13], v[78:79], v[130:131]
	global_store_dwordx2 v[92:93], v[130:131], off
	v_mul_f32_e32 v97, v5, v131
	v_fmac_f32_e32 v97, v4, v130
	v_mul_f32_e32 v132, v81, v98
	s_or_b32 s10, s2, 0x100
	s_mov_b32 s11, s3
	v_lshl_add_u64 v[92:93], s[10:11], 2, v[16:17]
	v_pk_mul_f32 v[132:133], v[2:3], v[132:133] op_sel_hi:[1,0]
	s_nop 0
	v_pk_fma_f32 v[132:133], v[12:13], v[76:77], v[132:133]
	global_store_dwordx2 v[92:93], v[132:133], off
	v_mul_f32_e32 v98, v5, v133
	v_fmac_f32_e32 v98, v4, v132
	v_mul_f32_e32 v134, v81, v99
	s_or_b32 s10, s2, 0x180
	s_mov_b32 s11, s3
	v_lshl_add_u64 v[92:93], s[10:11], 2, v[16:17]
	v_pk_mul_f32 v[134:135], v[2:3], v[134:135] op_sel_hi:[1,0]
	s_nop 0
	v_pk_fma_f32 v[134:135], v[12:13], v[74:75], v[134:135]
	global_store_dwordx2 v[92:93], v[134:135], off
	v_mul_f32_e32 v99, v5, v135
	v_fmac_f32_e32 v99, v4, v134
	v_mul_f32_e32 v136, v81, v100
	s_or_b32 s10, s2, 0x200
	s_mov_b32 s11, s3
	v_lshl_add_u64 v[92:93], s[10:11], 2, v[16:17]
	v_pk_mul_f32 v[136:137], v[2:3], v[136:137] op_sel_hi:[1,0]
	s_nop 0
	v_pk_fma_f32 v[136:137], v[12:13], v[72:73], v[136:137]
	global_store_dwordx2 v[92:93], v[136:137], off
	v_mul_f32_e32 v100, v5, v137
	v_fmac_f32_e32 v100, v4, v136
	v_mul_f32_e32 v138, v81, v101
	s_or_b32 s10, s2, 0x280
	s_mov_b32 s11, s3
	v_lshl_add_u64 v[92:93], s[10:11], 2, v[16:17]
	v_pk_mul_f32 v[138:139], v[2:3], v[138:139] op_sel_hi:[1,0]
	s_nop 0
	v_pk_fma_f32 v[138:139], v[12:13], v[70:71], v[138:139]
	global_store_dwordx2 v[92:93], v[138:139], off
	v_mul_f32_e32 v101, v5, v139
	v_fmac_f32_e32 v101, v4, v138
	v_mul_f32_e32 v140, v81, v102
	s_or_b32 s10, s2, 0x300
	s_mov_b32 s11, s3
	v_lshl_add_u64 v[92:93], s[10:11], 2, v[16:17]
	v_pk_mul_f32 v[140:141], v[2:3], v[140:141] op_sel_hi:[1,0]
	s_nop 0
	v_pk_fma_f32 v[140:141], v[12:13], v[68:69], v[140:141]
	global_store_dwordx2 v[92:93], v[140:141], off
	v_mul_f32_e32 v102, v5, v141
	v_fmac_f32_e32 v102, v4, v140
	v_mul_f32_e32 v142, v81, v103
	s_or_b32 s10, s2, 0x380
	s_mov_b32 s11, s3
	v_lshl_add_u64 v[92:93], s[10:11], 2, v[16:17]
	v_pk_mul_f32 v[142:143], v[2:3], v[142:143] op_sel_hi:[1,0]
	s_nop 0
	v_pk_fma_f32 v[142:143], v[12:13], v[64:65], v[142:143]
	global_store_dwordx2 v[92:93], v[142:143], off
	v_mul_f32_e32 v103, v5, v143
	v_fmac_f32_e32 v103, v4, v142
	v_mul_f32_e32 v144, v81, v104
	s_or_b32 s10, s2, 0x400
	s_mov_b32 s11, s3
	v_lshl_add_u64 v[92:93], s[10:11], 2, v[16:17]
	v_pk_mul_f32 v[144:145], v[2:3], v[144:145] op_sel_hi:[1,0]
	s_nop 0
	v_pk_fma_f32 v[144:145], v[12:13], v[66:67], v[144:145]
	global_store_dwordx2 v[92:93], v[144:145], off
	v_mul_f32_e32 v104, v5, v145
	v_fmac_f32_e32 v104, v4, v144
	v_mul_f32_e32 v146, v81, v105
	s_or_b32 s10, s2, 0x480
	s_mov_b32 s11, s3
	v_lshl_add_u64 v[92:93], s[10:11], 2, v[16:17]
	v_pk_mul_f32 v[146:147], v[2:3], v[146:147] op_sel_hi:[1,0]
	s_nop 0
	v_pk_fma_f32 v[146:147], v[12:13], v[62:63], v[146:147]
	global_store_dwordx2 v[92:93], v[146:147], off
	v_mul_f32_e32 v105, v5, v147
	v_fmac_f32_e32 v105, v4, v146
	v_mul_f32_e32 v148, v81, v106
	s_or_b32 s10, s2, 0x500
	s_mov_b32 s11, s3
	v_lshl_add_u64 v[92:93], s[10:11], 2, v[16:17]
	v_pk_mul_f32 v[148:149], v[2:3], v[148:149] op_sel_hi:[1,0]
	s_nop 0
	v_pk_fma_f32 v[148:149], v[12:13], v[60:61], v[148:149]
	global_store_dwordx2 v[92:93], v[148:149], off
	v_mul_f32_e32 v106, v5, v149
	v_fmac_f32_e32 v106, v4, v148
	v_mul_f32_e32 v150, v81, v107
	s_or_b32 s10, s2, 0x580
	s_mov_b32 s11, s3
	v_lshl_add_u64 v[92:93], s[10:11], 2, v[16:17]
	v_pk_mul_f32 v[150:151], v[2:3], v[150:151] op_sel_hi:[1,0]
	s_nop 0
	v_pk_fma_f32 v[150:151], v[12:13], v[58:59], v[150:151]
	global_store_dwordx2 v[92:93], v[150:151], off
	v_mul_f32_e32 v107, v5, v151
	v_fmac_f32_e32 v107, v4, v150
	v_mul_f32_e32 v152, v81, v108
	s_or_b32 s10, s2, 0x600
	s_mov_b32 s11, s3
	v_lshl_add_u64 v[92:93], s[10:11], 2, v[16:17]
	v_pk_mul_f32 v[152:153], v[2:3], v[152:153] op_sel_hi:[1,0]
	s_nop 0
	v_pk_fma_f32 v[152:153], v[12:13], v[56:57], v[152:153]
	global_store_dwordx2 v[92:93], v[152:153], off
	v_mul_f32_e32 v108, v5, v153
	v_fmac_f32_e32 v108, v4, v152
	v_mul_f32_e32 v154, v81, v109
	s_or_b32 s10, s2, 0x680
	s_mov_b32 s11, s3
	v_lshl_add_u64 v[92:93], s[10:11], 2, v[16:17]
	v_pk_mul_f32 v[154:155], v[2:3], v[154:155] op_sel_hi:[1,0]
	s_nop 0
	v_pk_fma_f32 v[154:155], v[12:13], v[54:55], v[154:155]
	global_store_dwordx2 v[92:93], v[154:155], off
	v_mul_f32_e32 v109, v5, v155
	v_fmac_f32_e32 v109, v4, v154
	v_mul_f32_e32 v156, v81, v110
	s_or_b32 s10, s2, 0x700
	s_mov_b32 s11, s3
	v_lshl_add_u64 v[92:93], s[10:11], 2, v[16:17]
	v_pk_mul_f32 v[156:157], v[2:3], v[156:157] op_sel_hi:[1,0]
	s_nop 0
	v_pk_fma_f32 v[156:157], v[12:13], v[52:53], v[156:157]
	global_store_dwordx2 v[92:93], v[156:157], off
	v_mul_f32_e32 v110, v5, v157
	v_fmac_f32_e32 v110, v4, v156
	v_mul_f32_e32 v158, v81, v111
	s_or_b32 s10, s2, 0x780
	s_mov_b32 s11, s3
	v_lshl_add_u64 v[92:93], s[10:11], 2, v[16:17]
	v_pk_mul_f32 v[158:159], v[2:3], v[158:159] op_sel_hi:[1,0]
	s_nop 0
	v_pk_fma_f32 v[158:159], v[12:13], v[50:51], v[158:159]
	global_store_dwordx2 v[92:93], v[158:159], off
	v_mul_f32_e32 v111, v5, v159
	v_fmac_f32_e32 v111, v4, v158
	v_mul_f32_e32 v160, v81, v112
	s_or_b32 s10, s2, 0x800
	s_mov_b32 s11, s3
	v_lshl_add_u64 v[92:93], s[10:11], 2, v[16:17]
	v_pk_mul_f32 v[160:161], v[2:3], v[160:161] op_sel_hi:[1,0]
	s_nop 0
	v_pk_fma_f32 v[160:161], v[12:13], v[48:49], v[160:161]
	global_store_dwordx2 v[92:93], v[160:161], off
	v_mul_f32_e32 v112, v5, v161
	v_fmac_f32_e32 v112, v4, v160
	v_mul_f32_e32 v162, v81, v113
	s_or_b32 s10, s2, 0x880
	s_mov_b32 s11, s3
	v_lshl_add_u64 v[92:93], s[10:11], 2, v[16:17]
	v_pk_mul_f32 v[162:163], v[2:3], v[162:163] op_sel_hi:[1,0]
	s_nop 0
	v_pk_fma_f32 v[162:163], v[12:13], v[46:47], v[162:163]
	global_store_dwordx2 v[92:93], v[162:163], off
	v_mul_f32_e32 v113, v5, v163
	v_fmac_f32_e32 v113, v4, v162
	v_mul_f32_e32 v164, v81, v114
	s_or_b32 s10, s2, 0x900
	s_mov_b32 s11, s3
	v_lshl_add_u64 v[92:93], s[10:11], 2, v[16:17]
	v_pk_mul_f32 v[164:165], v[2:3], v[164:165] op_sel_hi:[1,0]
	s_nop 0
	v_pk_fma_f32 v[164:165], v[12:13], v[44:45], v[164:165]
	global_store_dwordx2 v[92:93], v[164:165], off
	v_mul_f32_e32 v114, v5, v165
	v_fmac_f32_e32 v114, v4, v164
	v_mul_f32_e32 v166, v81, v115
	s_or_b32 s10, s2, 0x980
	s_mov_b32 s11, s3
	v_lshl_add_u64 v[92:93], s[10:11], 2, v[16:17]
	v_pk_mul_f32 v[166:167], v[2:3], v[166:167] op_sel_hi:[1,0]
	s_nop 0
	v_pk_fma_f32 v[166:167], v[12:13], v[42:43], v[166:167]
	global_store_dwordx2 v[92:93], v[166:167], off
	v_mul_f32_e32 v115, v5, v167
	v_fmac_f32_e32 v115, v4, v166
	v_mul_f32_e32 v168, v81, v116
	s_or_b32 s10, s2, 0xa00
	s_mov_b32 s11, s3
	v_lshl_add_u64 v[92:93], s[10:11], 2, v[16:17]
	v_pk_mul_f32 v[168:169], v[2:3], v[168:169] op_sel_hi:[1,0]
	s_nop 0
	v_pk_fma_f32 v[168:169], v[12:13], v[40:41], v[168:169]
	global_store_dwordx2 v[92:93], v[168:169], off
	v_mul_f32_e32 v116, v5, v169
	v_fmac_f32_e32 v116, v4, v168
	v_mul_f32_e32 v170, v81, v117
	s_or_b32 s10, s2, 0xa80
	s_mov_b32 s11, s3
	v_lshl_add_u64 v[92:93], s[10:11], 2, v[16:17]
	v_pk_mul_f32 v[170:171], v[2:3], v[170:171] op_sel_hi:[1,0]
	s_nop 0
	v_pk_fma_f32 v[170:171], v[12:13], v[38:39], v[170:171]
	global_store_dwordx2 v[92:93], v[170:171], off
	v_mul_f32_e32 v117, v5, v171
	v_fmac_f32_e32 v117, v4, v170
	v_mul_f32_e32 v172, v81, v118
	s_or_b32 s10, s2, 0xb00
	s_mov_b32 s11, s3
	v_lshl_add_u64 v[92:93], s[10:11], 2, v[16:17]
	v_pk_mul_f32 v[172:173], v[2:3], v[172:173] op_sel_hi:[1,0]
	s_nop 0
	v_pk_fma_f32 v[172:173], v[12:13], v[36:37], v[172:173]
	global_store_dwordx2 v[92:93], v[172:173], off
	v_mul_f32_e32 v118, v5, v173
	v_fmac_f32_e32 v118, v4, v172
	v_mul_f32_e32 v174, v81, v119
	s_or_b32 s10, s2, 0xb80
	s_mov_b32 s11, s3
	v_lshl_add_u64 v[92:93], s[10:11], 2, v[16:17]
	v_pk_mul_f32 v[174:175], v[2:3], v[174:175] op_sel_hi:[1,0]
	s_nop 0
	v_pk_fma_f32 v[174:175], v[12:13], v[34:35], v[174:175]
	global_store_dwordx2 v[92:93], v[174:175], off
	v_mul_f32_e32 v119, v5, v175
	v_fmac_f32_e32 v119, v4, v174
	v_mul_f32_e32 v176, v81, v120
	s_or_b32 s10, s2, 0xc00
	s_mov_b32 s11, s3
	v_lshl_add_u64 v[92:93], s[10:11], 2, v[16:17]
	v_pk_mul_f32 v[176:177], v[2:3], v[176:177] op_sel_hi:[1,0]
	s_nop 0
	v_pk_fma_f32 v[176:177], v[12:13], v[32:33], v[176:177]
	global_store_dwordx2 v[92:93], v[176:177], off
	v_mul_f32_e32 v120, v5, v177
	v_fmac_f32_e32 v120, v4, v176
	v_mul_f32_e32 v178, v81, v121
	s_or_b32 s10, s2, 0xc80
	s_mov_b32 s11, s3
	v_lshl_add_u64 v[92:93], s[10:11], 2, v[16:17]
	v_pk_mul_f32 v[178:179], v[2:3], v[178:179] op_sel_hi:[1,0]
	s_nop 0
	v_pk_fma_f32 v[178:179], v[12:13], v[30:31], v[178:179]
	global_store_dwordx2 v[92:93], v[178:179], off
	v_mul_f32_e32 v121, v5, v179
	v_fmac_f32_e32 v121, v4, v178
	v_mul_f32_e32 v180, v81, v122
	s_or_b32 s10, s2, 0xd00
	s_mov_b32 s11, s3
	v_lshl_add_u64 v[92:93], s[10:11], 2, v[16:17]
	v_pk_mul_f32 v[180:181], v[2:3], v[180:181] op_sel_hi:[1,0]
	s_nop 0
	v_pk_fma_f32 v[180:181], v[12:13], v[28:29], v[180:181]
	global_store_dwordx2 v[92:93], v[180:181], off
	v_mul_f32_e32 v122, v5, v181
	v_fmac_f32_e32 v122, v4, v180
	v_mul_f32_e32 v182, v81, v123
	s_or_b32 s10, s2, 0xd80
	s_mov_b32 s11, s3
	v_lshl_add_u64 v[92:93], s[10:11], 2, v[16:17]
	v_pk_mul_f32 v[182:183], v[2:3], v[182:183] op_sel_hi:[1,0]
	s_nop 0
	v_pk_fma_f32 v[182:183], v[12:13], v[26:27], v[182:183]
	global_store_dwordx2 v[92:93], v[182:183], off
	v_mul_f32_e32 v123, v5, v183
	v_fmac_f32_e32 v123, v4, v182
	v_mul_f32_e32 v184, v81, v124
	s_or_b32 s10, s2, 0xe00
	s_mov_b32 s11, s3
	v_lshl_add_u64 v[92:93], s[10:11], 2, v[16:17]
	v_pk_mul_f32 v[184:185], v[2:3], v[184:185] op_sel_hi:[1,0]
	s_nop 0
	v_pk_fma_f32 v[184:185], v[12:13], v[24:25], v[184:185]
	global_store_dwordx2 v[92:93], v[184:185], off
	v_mul_f32_e32 v124, v5, v185
	v_fmac_f32_e32 v124, v4, v184
	v_mul_f32_e32 v186, v81, v125
	s_or_b32 s10, s2, 0xe80
	s_mov_b32 s11, s3
	v_lshl_add_u64 v[92:93], s[10:11], 2, v[16:17]
	v_pk_mul_f32 v[186:187], v[2:3], v[186:187] op_sel_hi:[1,0]
	s_nop 0
	v_pk_fma_f32 v[186:187], v[12:13], v[22:23], v[186:187]
	global_store_dwordx2 v[92:93], v[186:187], off
	v_mul_f32_e32 v125, v5, v187
	v_fmac_f32_e32 v125, v4, v186
	v_mul_f32_e32 v188, v81, v126
	s_or_b32 s10, s2, 0xf00
	s_mov_b32 s11, s3
	v_lshl_add_u64 v[92:93], s[10:11], 2, v[16:17]
	v_pk_mul_f32 v[188:189], v[2:3], v[188:189] op_sel_hi:[1,0]
	s_nop 0
	v_pk_fma_f32 v[188:189], v[12:13], v[20:21], v[188:189]
	global_store_dwordx2 v[92:93], v[188:189], off
	v_mul_f32_e32 v126, v5, v189
	v_fmac_f32_e32 v126, v4, v188
	v_mul_f32_e32 v190, v81, v127
	s_or_b32 s10, s2, 0xf80
	s_mov_b32 s11, s3
	v_lshl_add_u64 v[92:93], s[10:11], 2, v[16:17]
	v_pk_mul_f32 v[190:191], v[2:3], v[190:191] op_sel_hi:[1,0]
	s_nop 0
	v_pk_fma_f32 v[190:191], v[12:13], v[18:19], v[190:191]
	global_store_dwordx2 v[92:93], v[190:191], off
	v_mul_f32_e32 v127, v5, v191
	v_fmac_f32_e32 v127, v4, v190
	ds_bpermute_b32 v128, v0, v96
	ds_bpermute_b32 v129, v0, v97
	ds_bpermute_b32 v130, v0, v98
	ds_bpermute_b32 v131, v0, v99
	ds_bpermute_b32 v132, v0, v100
	ds_bpermute_b32 v133, v0, v101
	ds_bpermute_b32 v134, v0, v102
	ds_bpermute_b32 v135, v0, v103
	ds_bpermute_b32 v136, v0, v104
	ds_bpermute_b32 v137, v0, v105
	ds_bpermute_b32 v138, v0, v106
	ds_bpermute_b32 v139, v0, v107
	ds_bpermute_b32 v140, v0, v108
	ds_bpermute_b32 v141, v0, v109
	ds_bpermute_b32 v142, v0, v110
	ds_bpermute_b32 v143, v0, v111
	s_waitcnt lgkmcnt(0)
	v_add_f32_e32 v96, v96, v128
	v_add_f32_e32 v97, v97, v129
	v_add_f32_e32 v98, v98, v130
	v_add_f32_e32 v99, v99, v131
	v_add_f32_e32 v100, v100, v132
	v_add_f32_e32 v101, v101, v133
	v_add_f32_e32 v102, v102, v134
	v_add_f32_e32 v103, v103, v135
	v_add_f32_e32 v104, v104, v136
	v_add_f32_e32 v105, v105, v137
	v_add_f32_e32 v106, v106, v138
	v_add_f32_e32 v107, v107, v139
	v_add_f32_e32 v108, v108, v140
	v_add_f32_e32 v109, v109, v141
	v_add_f32_e32 v110, v110, v142
	v_add_f32_e32 v111, v111, v143
	ds_bpermute_b32 v128, v0, v112
	ds_bpermute_b32 v129, v0, v113
	ds_bpermute_b32 v130, v0, v114
	ds_bpermute_b32 v131, v0, v115
	ds_bpermute_b32 v132, v0, v116
	ds_bpermute_b32 v133, v0, v117
	ds_bpermute_b32 v134, v0, v118
	ds_bpermute_b32 v135, v0, v119
	ds_bpermute_b32 v136, v0, v120
	ds_bpermute_b32 v137, v0, v121
	ds_bpermute_b32 v138, v0, v122
	ds_bpermute_b32 v139, v0, v123
	ds_bpermute_b32 v140, v0, v124
	ds_bpermute_b32 v141, v0, v125
	ds_bpermute_b32 v142, v0, v126
	ds_bpermute_b32 v143, v0, v127
	s_waitcnt lgkmcnt(0)
	v_add_f32_e32 v112, v112, v128
	v_add_f32_e32 v113, v113, v129
	v_add_f32_e32 v114, v114, v130
	v_add_f32_e32 v115, v115, v131
	v_add_f32_e32 v116, v116, v132
	v_add_f32_e32 v117, v117, v133
	v_add_f32_e32 v118, v118, v134
	v_add_f32_e32 v119, v119, v135
	v_add_f32_e32 v120, v120, v136
	v_add_f32_e32 v121, v121, v137
	v_add_f32_e32 v122, v122, v138
	v_add_f32_e32 v123, v123, v139
	v_add_f32_e32 v124, v124, v140
	v_add_f32_e32 v125, v125, v141
	v_add_f32_e32 v126, v126, v142
	v_add_f32_e32 v127, v127, v143
	ds_bpermute_b32 v128, v82, v96
	ds_bpermute_b32 v129, v82, v97
	ds_bpermute_b32 v130, v82, v98
	ds_bpermute_b32 v131, v82, v99
	ds_bpermute_b32 v132, v82, v100
	ds_bpermute_b32 v133, v82, v101
	ds_bpermute_b32 v134, v82, v102
	ds_bpermute_b32 v135, v82, v103
	ds_bpermute_b32 v136, v82, v104
	ds_bpermute_b32 v137, v82, v105
	ds_bpermute_b32 v138, v82, v106
	ds_bpermute_b32 v139, v82, v107
	ds_bpermute_b32 v140, v82, v108
	ds_bpermute_b32 v141, v82, v109
	ds_bpermute_b32 v142, v82, v110
	ds_bpermute_b32 v143, v82, v111
	s_waitcnt lgkmcnt(0)
	v_add_f32_e32 v96, v96, v128
	v_add_f32_e32 v97, v97, v129
	v_add_f32_e32 v98, v98, v130
	v_add_f32_e32 v99, v99, v131
	v_add_f32_e32 v100, v100, v132
	v_add_f32_e32 v101, v101, v133
	v_add_f32_e32 v102, v102, v134
	v_add_f32_e32 v103, v103, v135
	v_add_f32_e32 v104, v104, v136
	v_add_f32_e32 v105, v105, v137
	v_add_f32_e32 v106, v106, v138
	v_add_f32_e32 v107, v107, v139
	v_add_f32_e32 v108, v108, v140
	v_add_f32_e32 v109, v109, v141
	v_add_f32_e32 v110, v110, v142
	v_add_f32_e32 v111, v111, v143
	ds_bpermute_b32 v128, v82, v112
	ds_bpermute_b32 v129, v82, v113
	ds_bpermute_b32 v130, v82, v114
	ds_bpermute_b32 v131, v82, v115
	ds_bpermute_b32 v132, v82, v116
	ds_bpermute_b32 v133, v82, v117
	ds_bpermute_b32 v134, v82, v118
	ds_bpermute_b32 v135, v82, v119
	ds_bpermute_b32 v136, v82, v120
	ds_bpermute_b32 v137, v82, v121
	ds_bpermute_b32 v138, v82, v122
	ds_bpermute_b32 v139, v82, v123
	ds_bpermute_b32 v140, v82, v124
	ds_bpermute_b32 v141, v82, v125
	ds_bpermute_b32 v142, v82, v126
	ds_bpermute_b32 v143, v82, v127
	s_waitcnt lgkmcnt(0)
	v_add_f32_e32 v112, v112, v128
	v_add_f32_e32 v113, v113, v129
	v_add_f32_e32 v114, v114, v130
	v_add_f32_e32 v115, v115, v131
	v_add_f32_e32 v116, v116, v132
	v_add_f32_e32 v117, v117, v133
	v_add_f32_e32 v118, v118, v134
	v_add_f32_e32 v119, v119, v135
	v_add_f32_e32 v120, v120, v136
	v_add_f32_e32 v121, v121, v137
	v_add_f32_e32 v122, v122, v138
	v_add_f32_e32 v123, v123, v139
	v_add_f32_e32 v124, v124, v140
	v_add_f32_e32 v125, v125, v141
	v_add_f32_e32 v126, v126, v142
	v_add_f32_e32 v127, v127, v143
	ds_bpermute_b32 v128, v83, v96
	ds_bpermute_b32 v129, v83, v97
	ds_bpermute_b32 v130, v83, v98
	ds_bpermute_b32 v131, v83, v99
	ds_bpermute_b32 v132, v83, v100
	ds_bpermute_b32 v133, v83, v101
	ds_bpermute_b32 v134, v83, v102
	ds_bpermute_b32 v135, v83, v103
	ds_bpermute_b32 v136, v83, v104
	ds_bpermute_b32 v137, v83, v105
	ds_bpermute_b32 v138, v83, v106
	ds_bpermute_b32 v139, v83, v107
	ds_bpermute_b32 v140, v83, v108
	ds_bpermute_b32 v141, v83, v109
	ds_bpermute_b32 v142, v83, v110
	ds_bpermute_b32 v143, v83, v111
	s_waitcnt lgkmcnt(0)
	v_add_f32_e32 v96, v96, v128
	v_add_f32_e32 v97, v97, v129
	v_add_f32_e32 v98, v98, v130
	v_add_f32_e32 v99, v99, v131
	v_add_f32_e32 v100, v100, v132
	v_add_f32_e32 v101, v101, v133
	v_add_f32_e32 v102, v102, v134
	v_add_f32_e32 v103, v103, v135
	v_add_f32_e32 v104, v104, v136
	v_add_f32_e32 v105, v105, v137
	v_add_f32_e32 v106, v106, v138
	v_add_f32_e32 v107, v107, v139
	v_add_f32_e32 v108, v108, v140
	v_add_f32_e32 v109, v109, v141
	v_add_f32_e32 v110, v110, v142
	v_add_f32_e32 v111, v111, v143
	ds_bpermute_b32 v128, v83, v112
	ds_bpermute_b32 v129, v83, v113
	ds_bpermute_b32 v130, v83, v114
	ds_bpermute_b32 v131, v83, v115
	ds_bpermute_b32 v132, v83, v116
	ds_bpermute_b32 v133, v83, v117
	ds_bpermute_b32 v134, v83, v118
	ds_bpermute_b32 v135, v83, v119
	ds_bpermute_b32 v136, v83, v120
	ds_bpermute_b32 v137, v83, v121
	ds_bpermute_b32 v138, v83, v122
	ds_bpermute_b32 v139, v83, v123
	ds_bpermute_b32 v140, v83, v124
	ds_bpermute_b32 v141, v83, v125
	ds_bpermute_b32 v142, v83, v126
	ds_bpermute_b32 v143, v83, v127
	s_waitcnt lgkmcnt(0)
	v_add_f32_e32 v112, v112, v128
	v_add_f32_e32 v113, v113, v129
	v_add_f32_e32 v114, v114, v130
	v_add_f32_e32 v115, v115, v131
	v_add_f32_e32 v116, v116, v132
	v_add_f32_e32 v117, v117, v133
	v_add_f32_e32 v118, v118, v134
	v_add_f32_e32 v119, v119, v135
	v_add_f32_e32 v120, v120, v136
	v_add_f32_e32 v121, v121, v137
	v_add_f32_e32 v122, v122, v138
	v_add_f32_e32 v123, v123, v139
	v_add_f32_e32 v124, v124, v140
	v_add_f32_e32 v125, v125, v141
	v_add_f32_e32 v126, v126, v142
	v_add_f32_e32 v127, v127, v143
	ds_bpermute_b32 v128, v84, v96
	ds_bpermute_b32 v129, v84, v97
	ds_bpermute_b32 v130, v84, v98
	ds_bpermute_b32 v131, v84, v99
	ds_bpermute_b32 v132, v84, v100
	ds_bpermute_b32 v133, v84, v101
	ds_bpermute_b32 v134, v84, v102
	ds_bpermute_b32 v135, v84, v103
	ds_bpermute_b32 v136, v84, v104
	ds_bpermute_b32 v137, v84, v105
	ds_bpermute_b32 v138, v84, v106
	ds_bpermute_b32 v139, v84, v107
	ds_bpermute_b32 v140, v84, v108
	ds_bpermute_b32 v141, v84, v109
	ds_bpermute_b32 v142, v84, v110
	ds_bpermute_b32 v143, v84, v111
	s_waitcnt lgkmcnt(0)
	v_add_f32_e32 v96, v96, v128
	v_add_f32_e32 v97, v97, v129
	v_add_f32_e32 v98, v98, v130
	v_add_f32_e32 v99, v99, v131
	v_add_f32_e32 v100, v100, v132
	v_add_f32_e32 v101, v101, v133
	v_add_f32_e32 v102, v102, v134
	v_add_f32_e32 v103, v103, v135
	v_add_f32_e32 v104, v104, v136
	v_add_f32_e32 v105, v105, v137
	v_add_f32_e32 v106, v106, v138
	v_add_f32_e32 v107, v107, v139
	v_add_f32_e32 v108, v108, v140
	v_add_f32_e32 v109, v109, v141
	v_add_f32_e32 v110, v110, v142
	v_add_f32_e32 v111, v111, v143
	ds_bpermute_b32 v128, v84, v112
	ds_bpermute_b32 v129, v84, v113
	ds_bpermute_b32 v130, v84, v114
	ds_bpermute_b32 v131, v84, v115
	ds_bpermute_b32 v132, v84, v116
	ds_bpermute_b32 v133, v84, v117
	ds_bpermute_b32 v134, v84, v118
	ds_bpermute_b32 v135, v84, v119
	ds_bpermute_b32 v136, v84, v120
	ds_bpermute_b32 v137, v84, v121
	ds_bpermute_b32 v138, v84, v122
	ds_bpermute_b32 v139, v84, v123
	ds_bpermute_b32 v140, v84, v124
	ds_bpermute_b32 v141, v84, v125
	ds_bpermute_b32 v142, v84, v126
	ds_bpermute_b32 v143, v84, v127
	s_waitcnt lgkmcnt(0)
	v_add_f32_e32 v112, v112, v128
	v_add_f32_e32 v113, v113, v129
	v_add_f32_e32 v114, v114, v130
	v_add_f32_e32 v115, v115, v131
	v_add_f32_e32 v116, v116, v132
	v_add_f32_e32 v117, v117, v133
	v_add_f32_e32 v118, v118, v134
	v_add_f32_e32 v119, v119, v135
	v_add_f32_e32 v120, v120, v136
	v_add_f32_e32 v121, v121, v137
	v_add_f32_e32 v122, v122, v138
	v_add_f32_e32 v123, v123, v139
	v_add_f32_e32 v124, v124, v140
	v_add_f32_e32 v125, v125, v141
	v_add_f32_e32 v126, v126, v142
	v_add_f32_e32 v127, v127, v143
	ds_bpermute_b32 v128, v85, v96
	ds_bpermute_b32 v129, v85, v97
	ds_bpermute_b32 v130, v85, v98
	ds_bpermute_b32 v131, v85, v99
	ds_bpermute_b32 v132, v85, v100
	ds_bpermute_b32 v133, v85, v101
	ds_bpermute_b32 v134, v85, v102
	ds_bpermute_b32 v135, v85, v103
	ds_bpermute_b32 v136, v85, v104
	ds_bpermute_b32 v137, v85, v105
	ds_bpermute_b32 v138, v85, v106
	ds_bpermute_b32 v139, v85, v107
	ds_bpermute_b32 v140, v85, v108
	ds_bpermute_b32 v141, v85, v109
	ds_bpermute_b32 v142, v85, v110
	ds_bpermute_b32 v143, v85, v111
	s_waitcnt lgkmcnt(0)
	v_add_f32_e32 v96, v96, v128
	v_add_f32_e32 v97, v97, v129
	v_add_f32_e32 v98, v98, v130
	v_add_f32_e32 v99, v99, v131
	v_add_f32_e32 v100, v100, v132
	v_add_f32_e32 v101, v101, v133
	v_add_f32_e32 v102, v102, v134
	v_add_f32_e32 v103, v103, v135
	v_add_f32_e32 v104, v104, v136
	v_add_f32_e32 v105, v105, v137
	v_add_f32_e32 v106, v106, v138
	v_add_f32_e32 v107, v107, v139
	v_add_f32_e32 v108, v108, v140
	v_add_f32_e32 v109, v109, v141
	v_add_f32_e32 v110, v110, v142
	v_add_f32_e32 v111, v111, v143
	ds_bpermute_b32 v128, v85, v112
	ds_bpermute_b32 v129, v85, v113
	ds_bpermute_b32 v130, v85, v114
	ds_bpermute_b32 v131, v85, v115
	ds_bpermute_b32 v132, v85, v116
	ds_bpermute_b32 v133, v85, v117
	ds_bpermute_b32 v134, v85, v118
	ds_bpermute_b32 v135, v85, v119
	ds_bpermute_b32 v136, v85, v120
	ds_bpermute_b32 v137, v85, v121
	ds_bpermute_b32 v138, v85, v122
	ds_bpermute_b32 v139, v85, v123
	ds_bpermute_b32 v140, v85, v124
	ds_bpermute_b32 v141, v85, v125
	ds_bpermute_b32 v142, v85, v126
	ds_bpermute_b32 v143, v85, v127
	s_waitcnt lgkmcnt(0)
	v_add_f32_e32 v112, v112, v128
	v_add_f32_e32 v113, v113, v129
	v_add_f32_e32 v114, v114, v130
	v_add_f32_e32 v115, v115, v131
	v_add_f32_e32 v116, v116, v132
	v_add_f32_e32 v117, v117, v133
	v_add_f32_e32 v118, v118, v134
	v_add_f32_e32 v119, v119, v135
	v_add_f32_e32 v120, v120, v136
	v_add_f32_e32 v121, v121, v137
	v_add_f32_e32 v122, v122, v138
	v_add_f32_e32 v123, v123, v139
	v_add_f32_e32 v124, v124, v140
	v_add_f32_e32 v125, v125, v141
	v_add_f32_e32 v126, v126, v142
	v_add_f32_e32 v127, v127, v143
	ds_bpermute_b32 v128, v86, v96
	ds_bpermute_b32 v129, v86, v97
	ds_bpermute_b32 v130, v86, v98
	ds_bpermute_b32 v131, v86, v99
	ds_bpermute_b32 v132, v86, v100
	ds_bpermute_b32 v133, v86, v101
	ds_bpermute_b32 v134, v86, v102
	ds_bpermute_b32 v135, v86, v103
	ds_bpermute_b32 v136, v86, v104
	ds_bpermute_b32 v137, v86, v105
	ds_bpermute_b32 v138, v86, v106
	ds_bpermute_b32 v139, v86, v107
	ds_bpermute_b32 v140, v86, v108
	ds_bpermute_b32 v141, v86, v109
	ds_bpermute_b32 v142, v86, v110
	ds_bpermute_b32 v143, v86, v111
	s_waitcnt lgkmcnt(0)
	v_add_f32_e32 v96, v96, v128
	v_add_f32_e32 v97, v97, v129
	v_add_f32_e32 v98, v98, v130
	v_add_f32_e32 v99, v99, v131
	v_add_f32_e32 v100, v100, v132
	v_add_f32_e32 v101, v101, v133
	v_add_f32_e32 v102, v102, v134
	v_add_f32_e32 v103, v103, v135
	v_add_f32_e32 v104, v104, v136
	v_add_f32_e32 v105, v105, v137
	v_add_f32_e32 v106, v106, v138
	v_add_f32_e32 v107, v107, v139
	v_add_f32_e32 v108, v108, v140
	v_add_f32_e32 v109, v109, v141
	v_add_f32_e32 v110, v110, v142
	v_add_f32_e32 v111, v111, v143
	ds_bpermute_b32 v128, v86, v112
	ds_bpermute_b32 v129, v86, v113
	ds_bpermute_b32 v130, v86, v114
	ds_bpermute_b32 v131, v86, v115
	ds_bpermute_b32 v132, v86, v116
	ds_bpermute_b32 v133, v86, v117
	ds_bpermute_b32 v134, v86, v118
	ds_bpermute_b32 v135, v86, v119
	ds_bpermute_b32 v136, v86, v120
	ds_bpermute_b32 v137, v86, v121
	ds_bpermute_b32 v138, v86, v122
	ds_bpermute_b32 v139, v86, v123
	ds_bpermute_b32 v140, v86, v124
	ds_bpermute_b32 v141, v86, v125
	ds_bpermute_b32 v142, v86, v126
	ds_bpermute_b32 v143, v86, v127
	s_waitcnt lgkmcnt(0)
	v_add_f32_e32 v112, v112, v128
	v_add_f32_e32 v113, v113, v129
	v_add_f32_e32 v114, v114, v130
	v_add_f32_e32 v115, v115, v131
	v_add_f32_e32 v116, v116, v132
	v_add_f32_e32 v117, v117, v133
	v_add_f32_e32 v118, v118, v134
	v_add_f32_e32 v119, v119, v135
	v_add_f32_e32 v120, v120, v136
	v_add_f32_e32 v121, v121, v137
	v_add_f32_e32 v122, v122, v138
	v_add_f32_e32 v123, v123, v139
	v_add_f32_e32 v124, v124, v140
	v_add_f32_e32 v125, v125, v141
	v_add_f32_e32 v126, v126, v142
	v_add_f32_e32 v127, v127, v143
	s_and_saveexec_b64 s[10:11], s[4:5]
	ds_write_b32 v87, v96 offset:6144
	ds_write_b32 v87, v97 offset:6148
	ds_write_b32 v87, v98 offset:6152
	ds_write_b32 v87, v99 offset:6156
	ds_write_b32 v87, v100 offset:6160
	ds_write_b32 v87, v101 offset:6164
	ds_write_b32 v87, v102 offset:6168
	ds_write_b32 v87, v103 offset:6172
	ds_write_b32 v87, v104 offset:6176
	ds_write_b32 v87, v105 offset:6180
	ds_write_b32 v87, v106 offset:6184
	ds_write_b32 v87, v107 offset:6188
	ds_write_b32 v87, v108 offset:6192
	ds_write_b32 v87, v109 offset:6196
	ds_write_b32 v87, v110 offset:6200
	ds_write_b32 v87, v111 offset:6204
	ds_write_b32 v87, v112 offset:6208
	ds_write_b32 v87, v113 offset:6212
	ds_write_b32 v87, v114 offset:6216
	ds_write_b32 v87, v115 offset:6220
	ds_write_b32 v87, v116 offset:6224
	ds_write_b32 v87, v117 offset:6228
	ds_write_b32 v87, v118 offset:6232
	ds_write_b32 v87, v119 offset:6236
	ds_write_b32 v87, v120 offset:6240
	ds_write_b32 v87, v121 offset:6244
	ds_write_b32 v87, v122 offset:6248
	ds_write_b32 v87, v123 offset:6252
	ds_write_b32 v87, v124 offset:6256
	ds_write_b32 v87, v125 offset:6260
	ds_write_b32 v87, v126 offset:6264
	ds_write_b32 v87, v127 offset:6268
	s_branch .LBB0_333
	s_nop 0
